# phase 4 order swap by whole attention (batch,head) groups: workgroups with (blockIdx>>7)&1 run retention before attention
# speedup vs baseline: 1.0018x; 1.0018x over previous
.Lp4_attn_entry:
	s_mov_b32 s0, s35
	s_mov_b32 s1, s98
	s_mov_b32 s4, -1
	v_mbcnt_lo_u32_b32 v0, -1, 0
	v_readlane_b32 s6, v252, 0
	v_mbcnt_hi_u32_b32 v0, s4, v0
	v_lshl_add_u32 v2, s1, 6, v0
	s_cmpk_gt_i32 s6, 0x4ff
	v_readfirstlane_b32 s4, v2
	s_cbranch_scc1 .LBB0_43
	v_readlane_b32 s5, v255, 62
	s_nop 3
	s_cmp_eq_u32 s5, 2
	s_cbranch_scc1 .Lp4_go_attn
	s_bfe_u32 s5, s6, 0x10007
	s_nop 0
	v_writelane_b32 v255, s5, 62
	s_cmp_eq_u32 s5, 1
	s_cbranch_scc1 .LBB0_43
